# cmp_item: QK and PV LDS fragment reads issued in batches of 4/8 before their MFMAs with counted lgkmcnt waits (was read-wait-mfma per fragment)
# speedup vs baseline: 1.0041x; 1.0041x over previous
; #define LAS __attribute__((address_space(3)))
; DI f32x4 zero4() { float a, b, c, d; asm volatile("v_mov_b32 %0, 0\n\tv_mov_b32 %1, 0\n\tv_mov_b32 %2, 0\n\tv_mov_b32 %3, 0\n\ts_nop 1" : "=v"(a), "=v"(b), "=v"(c), "=v"(d)); return (f32x4){a, b, c, d}; }
; DI unsigned char* WSP(const Params& p) { GAS unsigned char* w = (GAS unsigned char*)p.ws; asm volatile("" : "+s"(w)); return (unsigned char*)w; }
; DI void cmp_item(const Params& p, int item, LAS unsigned char* lds, int tid) {
;     const int bg = item & 15, traw = item >> 4, tile = ((traw >> 4) & 1) ? ((traw & ~15) | (15 - (traw & 15))) : traw, b = bg >> 1, g = bg & 1;
;     const int w = tid >> 6, lane = tid & 63, i16 = lane & 15, quad = lane >> 4;
;     const bf16_t* proj = (const bf16_t*)(WSP(p) + WS_BIG);
;     const LAS bf16_t* kcL = (const LAS bf16_t*)lds;
;     const LAS bf16_t* vcL = kcL + 256 * 136;
;     bf16_t* mix = (bf16_t*)(WSP(p) + WS_XN);
;     const int t0 = tile * 32 + w * 4, tl = i16 >> 2, hh = i16 & 3, t = t0 + tl;
;     const bf16_t* qptr = proj + (size_t)(b * T + t) * NINP + C_Q + (g * 4 + hh) * 128 + quad * 8;
;     bf16x8 q[4];
; #pragma unroll
;     for (int kk = 0; kk < 4; ++kk) q[kk] = *(const bf16x8*)(qptr + kk * 32);
;     const bf16_t gate_raw = proj[(size_t)(b * T + t) * NINP + C_G + (g * 4 + hh) * 3 + 0];
;     const int tmax = t0 + 3;
;     const int nvmax = (tmax >= 31) ? ((tmax - 31) >> 4) + 1 : 0;
;     const int ntile = (nvmax + 15) >> 4;
;     const int nv = (t >= 31) ? ((t - 31) >> 4) + 1 : 0;
;     constexpr float SC2 = ATT_SCALE * 1.4426950408889634f;
;     f32x4 acc[16];
; #pragma unroll
;     for (int a = 0; a < 16; ++a) { acc[a] = zero4();
;         if (a < ntile) {
; #pragma unroll
;             for (int kk = 0; kk < 4; ++kk) { const bf16x8 av = *(const LAS bf16x8*)(kcL + (a * 16 + i16) * 136 + kk * 32 + quad * 8);
;                 acc[a] = __builtin_amdgcn_mfma_f32_16x16x32_bf16(av, q[kk], acc[a], 0, 0, 0); } } }
.LBB0_104:
	s_lshl_b32 s5, s2, 1
	s_and_b32 s6, s5, 0xffffffe0
	s_and_b32 s4, s2, 0x100
	s_xor_b32 s7, s6, 0x1e0
	s_cmp_eq_u32 s4, 0
	v_ashrrev_i32_e32 v111, 6, v0
	s_cselect_b32 s6, s6, s7
	v_lshl_add_u32 v108, v111, 2, s6
	v_bfe_u32 v110, v109, 2, 2
	s_lshl_b32 s6, s80, 11
	s_mov_b64 s[4:5], s[28:29]
	v_or_b32_e32 v82, v108, v110
	s_and_b32 s6, s6, 0x7000
	v_add_u32_e32 v80, s6, v82
	v_mov_b64_e32 v[0:1], s[4:5]
	v_mad_i64_i32 v[0:1], s[4:5], v80, s96, v[0:1]
	s_mov_b64 s[4:5], 0x1be00000
	v_and_b32_e32 v112, 3, v109
	v_lshl_add_u64 v[8:9], v[0:1], 0, s[4:5]
	s_lshl_b32 s4, s2, 2
	v_and_or_b32 v83, s4, 4, v112
	v_lshlrev_b32_e32 v198, 8, v83
	v_mul_u32_u24_e32 v10, 3, v83
	v_lshl_add_u64 v[0:1], v[8:9], 0, v[198:199]
	v_and_b32_e32 v198, 48, v109
	v_lshlrev_b32_e32 v10, 1, v10
	v_mov_b32_e32 v11, v199
	s_mov_b64 s[56:57], s[28:29]
	v_lshl_add_u64 v[0:1], v[0:1], 0, v[198:199]
	v_lshl_add_u64 v[8:9], v[8:9], 0, v[10:11]
	s_movk_i32 s4, 0x1000
	global_load_dwordx4 v[16:19], v[0:1], off
	global_load_dwordx4 v[12:15], v[0:1], off offset:64
	global_load_dwordx4 v[4:7], v[0:1], off offset:128
	s_nop 0
	global_load_dwordx4 v[0:3], v[0:1], off offset:192
	v_add_co_u32_e32 v8, vcc, s4, v8
	v_and_b32_e32 v106, 15, v109
	s_nop 0
	v_addc_co_u32_e32 v9, vcc, 0, v9, vcc
	global_load_ushort v81, v[8:9], off offset:1024
	v_subrev_u32_e32 v9, 28, v108
	v_ashrrev_i32_e32 v9, 4, v9
	v_or_b32_e32 v8, 3, v108
	v_add_u32_e32 v9, 16, v9
	v_ashrrev_i32_e32 v9, 4, v9
	v_cmp_lt_i32_e32 vcc, 30, v8
	s_waitcnt vmcnt(0)
	v_add_u32_e32 v20, 0, v198
	v_mad_u32_u24 v84, v106, s68, v20
	v_cndmask_b32_e32 v85, 0, v9, vcc
	v_cmp_lt_i32_e64 s[20:21], 0, v85
	v_mov_b32 v8, 0
	v_mov_b32 v9, 0
	v_mov_b32 v10, 0
	v_mov_b32 v11, 0
	s_nop 1
	s_and_saveexec_b64 s[6:7], s[20:21]
	s_cbranch_execz .LBB0_106
	ds_read_b128 v[130:133], v84
	ds_read_b128 v[134:137], v84 offset:64
	ds_read_b128 v[138:141], v84 offset:128
	ds_read_b128 v[142:145], v84 offset:192
	s_waitcnt vmcnt(0) lgkmcnt(3)
	v_mfma_f32_16x16x32_bf16 v[8:11], v[130:133], v[16:19], v[8:11]
	s_waitcnt lgkmcnt(2)
	v_mfma_f32_16x16x32_bf16 v[8:11], v[134:137], v[12:15], v[8:11]
	s_waitcnt lgkmcnt(1)
	v_mfma_f32_16x16x32_bf16 v[8:11], v[138:141], v[4:7], v[8:11]
	s_waitcnt lgkmcnt(0)
	v_mfma_f32_16x16x32_bf16 v[8:11], v[142:145], v[0:3], v[8:11]
.LBB0_106:
	s_or_b64 exec, exec, s[6:7]
	v_cmp_lt_i32_e32 vcc, 1, v85
	v_mov_b32 v20, 0
	v_mov_b32 v21, 0
	v_mov_b32 v22, 0
	v_mov_b32 v23, 0
	s_nop 1
	s_and_saveexec_b64 s[6:7], vcc
	s_cbranch_execz .LBB0_108
	ds_read_b128 v[146:149], v84 offset:4352
	ds_read_b128 v[150:153], v84 offset:4416
	ds_read_b128 v[154:157], v84 offset:4480
	ds_read_b128 v[158:161], v84 offset:4544
	s_waitcnt vmcnt(0) lgkmcnt(3)
	v_mfma_f32_16x16x32_bf16 v[20:23], v[146:149], v[16:19], v[20:23]
	s_waitcnt lgkmcnt(2)
	v_mfma_f32_16x16x32_bf16 v[20:23], v[150:153], v[12:15], v[20:23]
	s_waitcnt lgkmcnt(1)
	v_mfma_f32_16x16x32_bf16 v[20:23], v[154:157], v[4:7], v[20:23]
	s_waitcnt lgkmcnt(0)
	v_mfma_f32_16x16x32_bf16 v[20:23], v[158:161], v[0:3], v[20:23]
.LBB0_108:
	s_or_b64 exec, exec, s[6:7]
	v_cmp_lt_i32_e64 s[18:19], 2, v85
	v_mov_b32 v24, 0
	v_mov_b32 v25, 0
	v_mov_b32 v26, 0
	v_mov_b32 v27, 0
	s_nop 1
	s_and_saveexec_b64 s[6:7], s[18:19]
	s_cbranch_execz .LBB0_110
	ds_read_b128 v[130:133], v84 offset:8704
	ds_read_b128 v[134:137], v84 offset:8768
	ds_read_b128 v[138:141], v84 offset:8832
	ds_read_b128 v[142:145], v84 offset:8896
	s_waitcnt vmcnt(0) lgkmcnt(3)
	v_mfma_f32_16x16x32_bf16 v[24:27], v[130:133], v[16:19], v[24:27]
	s_waitcnt lgkmcnt(2)
	v_mfma_f32_16x16x32_bf16 v[24:27], v[134:137], v[12:15], v[24:27]
	s_waitcnt lgkmcnt(1)
	v_mfma_f32_16x16x32_bf16 v[24:27], v[138:141], v[4:7], v[24:27]
	s_waitcnt lgkmcnt(0)
	v_mfma_f32_16x16x32_bf16 v[24:27], v[142:145], v[0:3], v[24:27]
.LBB0_110:
	s_or_b64 exec, exec, s[6:7]
	v_cmp_lt_i32_e32 vcc, 3, v85
	v_mov_b32 v28, 0
	v_mov_b32 v29, 0
	v_mov_b32 v30, 0
	v_mov_b32 v31, 0
	s_nop 1
	s_and_saveexec_b64 s[6:7], vcc
	s_cbranch_execz .LBB0_112
	s_waitcnt vmcnt(0)
	ds_read_b128 v[146:149], v84 offset:13056
	ds_read_b128 v[150:153], v84 offset:13120
	ds_read_b128 v[154:157], v84 offset:13184
	ds_read_b128 v[158:161], v84 offset:13248
	s_waitcnt vmcnt(0) lgkmcnt(3)
	v_mfma_f32_16x16x32_bf16 v[28:31], v[146:149], v[16:19], v[28:31]
	s_waitcnt lgkmcnt(2)
	v_mfma_f32_16x16x32_bf16 v[28:31], v[150:153], v[12:15], v[28:31]
	s_waitcnt lgkmcnt(1)
	v_mfma_f32_16x16x32_bf16 v[28:31], v[154:157], v[4:7], v[28:31]
	s_waitcnt lgkmcnt(0)
	v_mfma_f32_16x16x32_bf16 v[28:31], v[158:161], v[0:3], v[28:31]
.LBB0_112:
	s_or_b64 exec, exec, s[6:7]
	v_cmp_lt_i32_e64 s[16:17], 4, v85
	s_waitcnt vmcnt(0)
	v_mov_b32 v32, 0
	v_mov_b32 v33, 0
	v_mov_b32 v34, 0
	v_mov_b32 v35, 0
	s_nop 1
	s_and_saveexec_b64 s[6:7], s[16:17]
	s_cbranch_execz .LBB0_114
	s_waitcnt vmcnt(0)
	ds_read_b128 v[130:133], v84 offset:17408
	ds_read_b128 v[134:137], v84 offset:17472
	ds_read_b128 v[138:141], v84 offset:17536
	ds_read_b128 v[142:145], v84 offset:17600
	s_waitcnt vmcnt(0) lgkmcnt(3)
	v_mfma_f32_16x16x32_bf16 v[32:35], v[130:133], v[16:19], v[32:35]
	s_waitcnt lgkmcnt(2)
	v_mfma_f32_16x16x32_bf16 v[32:35], v[134:137], v[12:15], v[32:35]
	s_waitcnt lgkmcnt(1)
	v_mfma_f32_16x16x32_bf16 v[32:35], v[138:141], v[4:7], v[32:35]
	s_waitcnt lgkmcnt(0)
	v_mfma_f32_16x16x32_bf16 v[32:35], v[142:145], v[0:3], v[32:35]
; #define LAS __attribute__((address_space(3)))
; DI f32x4 zero4() { float a, b, c, d; asm volatile("v_mov_b32 %0, 0\n\tv_mov_b32 %1, 0\n\tv_mov_b32 %2, 0\n\tv_mov_b32 %3, 0\n\ts_nop 1" : "=v"(a), "=v"(b), "=v"(c), "=v"(d)); return (f32x4){a, b, c, d}; }
; DI void cmp_item(const Params& p, int item, LAS unsigned char* lds, int tid) {
;     ...
;     for (int a = 0; a < 16; ++a) { acc[a] = zero4();
;         if (a < ntile) {
; #pragma unroll
;             for (int kk = 0; kk < 4; ++kk) { const bf16x8 av = *(const LAS bf16x8*)(kcL + (a * 16 + i16) * 136 + kk * 32 + quad * 8);
;                 acc[a] = __builtin_amdgcn_mfma_f32_16x16x32_bf16(av, q[kk], acc[a], 0, 0, 0); } } }
.LBB0_114:
	s_or_b64 exec, exec, s[6:7]
	v_cmp_lt_i32_e32 vcc, 5, v85
	s_waitcnt vmcnt(0)
	v_mov_b32 v36, 0
	v_mov_b32 v37, 0
	v_mov_b32 v38, 0
	v_mov_b32 v39, 0
	s_nop 1
	s_and_saveexec_b64 s[6:7], vcc
	s_cbranch_execz .LBB0_116
	ds_read_b128 v[146:149], v84 offset:21760
	ds_read_b128 v[150:153], v84 offset:21824
	ds_read_b128 v[154:157], v84 offset:21888
	ds_read_b128 v[158:161], v84 offset:21952
	s_waitcnt vmcnt(0) lgkmcnt(3)
	v_mfma_f32_16x16x32_bf16 v[36:39], v[146:149], v[16:19], v[36:39]
	s_waitcnt lgkmcnt(2)
	v_mfma_f32_16x16x32_bf16 v[36:39], v[150:153], v[12:15], v[36:39]
	s_waitcnt lgkmcnt(1)
	v_mfma_f32_16x16x32_bf16 v[36:39], v[154:157], v[4:7], v[36:39]
	s_waitcnt lgkmcnt(0)
	v_mfma_f32_16x16x32_bf16 v[36:39], v[158:161], v[0:3], v[36:39]
.LBB0_116:
	s_or_b64 exec, exec, s[6:7]
	v_cmp_lt_i32_e64 s[14:15], 6, v85
	v_mov_b32 v40, 0
	v_mov_b32 v41, 0
	v_mov_b32 v42, 0
	v_mov_b32 v43, 0
	s_nop 1
	s_and_saveexec_b64 s[6:7], s[14:15]
	s_cbranch_execz .LBB0_118
	ds_read_b128 v[130:133], v84 offset:26112
	ds_read_b128 v[134:137], v84 offset:26176
	ds_read_b128 v[138:141], v84 offset:26240
	ds_read_b128 v[142:145], v84 offset:26304
	s_waitcnt vmcnt(0) lgkmcnt(3)
	v_mfma_f32_16x16x32_bf16 v[40:43], v[130:133], v[16:19], v[40:43]
	s_waitcnt lgkmcnt(2)
	v_mfma_f32_16x16x32_bf16 v[40:43], v[134:137], v[12:15], v[40:43]
	s_waitcnt lgkmcnt(1)
	v_mfma_f32_16x16x32_bf16 v[40:43], v[138:141], v[4:7], v[40:43]
	s_waitcnt lgkmcnt(0)
	v_mfma_f32_16x16x32_bf16 v[40:43], v[142:145], v[0:3], v[40:43]
.LBB0_118:
	s_or_b64 exec, exec, s[6:7]
	v_cmp_lt_i32_e32 vcc, 7, v85
	v_mov_b32 v44, 0
	v_mov_b32 v45, 0
	v_mov_b32 v46, 0
	v_mov_b32 v47, 0
	s_nop 1
	s_and_saveexec_b64 s[6:7], vcc
	s_cbranch_execz .LBB0_120
	s_waitcnt vmcnt(0)
	ds_read_b128 v[146:149], v84 offset:30464
	ds_read_b128 v[150:153], v84 offset:30528
	ds_read_b128 v[154:157], v84 offset:30592
	ds_read_b128 v[158:161], v84 offset:30656
	s_waitcnt vmcnt(0) lgkmcnt(3)
	v_mfma_f32_16x16x32_bf16 v[44:47], v[146:149], v[16:19], v[44:47]
	s_waitcnt lgkmcnt(2)
	v_mfma_f32_16x16x32_bf16 v[44:47], v[150:153], v[12:15], v[44:47]
	s_waitcnt lgkmcnt(1)
	v_mfma_f32_16x16x32_bf16 v[44:47], v[154:157], v[4:7], v[44:47]
	s_waitcnt lgkmcnt(0)
	v_mfma_f32_16x16x32_bf16 v[44:47], v[158:161], v[0:3], v[44:47]
.LBB0_120:
	s_or_b64 exec, exec, s[6:7]
	v_cmp_lt_i32_e64 s[12:13], 8, v85
	s_waitcnt vmcnt(0)
	v_mov_b32 v48, 0
	v_mov_b32 v49, 0
	v_mov_b32 v50, 0
	v_mov_b32 v51, 0
	s_nop 1
	s_and_saveexec_b64 s[6:7], s[12:13]
	s_cbranch_execz .LBB0_122
	s_waitcnt vmcnt(0)
	ds_read_b128 v[130:133], v84 offset:34816
	ds_read_b128 v[134:137], v84 offset:34880
	ds_read_b128 v[138:141], v84 offset:34944
	ds_read_b128 v[142:145], v84 offset:35008
	s_waitcnt vmcnt(0) lgkmcnt(3)
	v_mfma_f32_16x16x32_bf16 v[48:51], v[130:133], v[16:19], v[48:51]
	s_waitcnt lgkmcnt(2)
	v_mfma_f32_16x16x32_bf16 v[48:51], v[134:137], v[12:15], v[48:51]
	s_waitcnt lgkmcnt(1)
	v_mfma_f32_16x16x32_bf16 v[48:51], v[138:141], v[4:7], v[48:51]
	s_waitcnt lgkmcnt(0)
	v_mfma_f32_16x16x32_bf16 v[48:51], v[142:145], v[0:3], v[48:51]
.LBB0_122:
	s_or_b64 exec, exec, s[6:7]
	v_cmp_lt_i32_e32 vcc, 9, v85
	s_waitcnt vmcnt(0)
	v_mov_b32 v52, 0
	v_mov_b32 v53, 0
	v_mov_b32 v54, 0
	v_mov_b32 v55, 0
	s_nop 1
	s_and_saveexec_b64 s[6:7], vcc
	s_cbranch_execz .LBB0_124
	ds_read_b128 v[146:149], v84 offset:39168
	ds_read_b128 v[150:153], v84 offset:39232
	ds_read_b128 v[154:157], v84 offset:39296
	ds_read_b128 v[158:161], v84 offset:39360
	s_waitcnt vmcnt(0) lgkmcnt(3)
	v_mfma_f32_16x16x32_bf16 v[52:55], v[146:149], v[16:19], v[52:55]
	s_waitcnt lgkmcnt(2)
	v_mfma_f32_16x16x32_bf16 v[52:55], v[150:153], v[12:15], v[52:55]
	s_waitcnt lgkmcnt(1)
	v_mfma_f32_16x16x32_bf16 v[52:55], v[154:157], v[4:7], v[52:55]
	s_waitcnt lgkmcnt(0)
	v_mfma_f32_16x16x32_bf16 v[52:55], v[158:161], v[0:3], v[52:55]
; #define LAS __attribute__((address_space(3)))
; DI f32x4 zero4() { float a, b, c, d; asm volatile("v_mov_b32 %0, 0\n\tv_mov_b32 %1, 0\n\tv_mov_b32 %2, 0\n\tv_mov_b32 %3, 0\n\ts_nop 1" : "=v"(a), "=v"(b), "=v"(c), "=v"(d)); return (f32x4){a, b, c, d}; }
; DI void cmp_item(const Params& p, int item, LAS unsigned char* lds, int tid) {
;     ...
;     for (int a = 0; a < 16; ++a) { acc[a] = zero4();
;         if (a < ntile) {
; #pragma unroll
;             for (int kk = 0; kk < 4; ++kk) { const bf16x8 av = *(const LAS bf16x8*)(kcL + (a * 16 + i16) * 136 + kk * 32 + quad * 8);
;                 acc[a] = __builtin_amdgcn_mfma_f32_16x16x32_bf16(av, q[kk], acc[a], 0, 0, 0); } } }
.LBB0_124:
	s_or_b64 exec, exec, s[6:7]
	v_cmp_lt_i32_e64 s[10:11], 10, v85
	v_mov_b32 v56, 0
	v_mov_b32 v57, 0
	v_mov_b32 v58, 0
	v_mov_b32 v59, 0
	s_nop 1
	s_and_saveexec_b64 s[6:7], s[10:11]
	s_cbranch_execz .LBB0_126
	ds_read_b128 v[130:133], v84 offset:43520
	ds_read_b128 v[134:137], v84 offset:43584
	ds_read_b128 v[138:141], v84 offset:43648
	ds_read_b128 v[142:145], v84 offset:43712
	s_waitcnt vmcnt(0) lgkmcnt(3)
	v_mfma_f32_16x16x32_bf16 v[56:59], v[130:133], v[16:19], v[56:59]
	s_waitcnt lgkmcnt(2)
	v_mfma_f32_16x16x32_bf16 v[56:59], v[134:137], v[12:15], v[56:59]
	s_waitcnt lgkmcnt(1)
	v_mfma_f32_16x16x32_bf16 v[56:59], v[138:141], v[4:7], v[56:59]
	s_waitcnt lgkmcnt(0)
	v_mfma_f32_16x16x32_bf16 v[56:59], v[142:145], v[0:3], v[56:59]
.LBB0_126:
	s_or_b64 exec, exec, s[6:7]
	v_cmp_lt_i32_e32 vcc, 11, v85
	v_mov_b32 v60, 0
	v_mov_b32 v61, 0
	v_mov_b32 v62, 0
	v_mov_b32 v63, 0
	s_nop 1
	s_and_saveexec_b64 s[6:7], vcc
	s_cbranch_execz .LBB0_128
	ds_read_b128 v[146:149], v84 offset:47872
	ds_read_b128 v[150:153], v84 offset:47936
	ds_read_b128 v[154:157], v84 offset:48000
	ds_read_b128 v[158:161], v84 offset:48064
	s_waitcnt vmcnt(0) lgkmcnt(3)
	v_mfma_f32_16x16x32_bf16 v[60:63], v[146:149], v[16:19], v[60:63]
	s_waitcnt lgkmcnt(2)
	v_mfma_f32_16x16x32_bf16 v[60:63], v[150:153], v[12:15], v[60:63]
	s_waitcnt lgkmcnt(1)
	v_mfma_f32_16x16x32_bf16 v[60:63], v[154:157], v[4:7], v[60:63]
	s_waitcnt lgkmcnt(0)
	v_mfma_f32_16x16x32_bf16 v[60:63], v[158:161], v[0:3], v[60:63]
.LBB0_128:
	s_or_b64 exec, exec, s[6:7]
	v_cmp_lt_i32_e64 s[8:9], 12, v85
	v_mov_b32 v64, 0
	v_mov_b32 v65, 0
	v_mov_b32 v66, 0
	v_mov_b32 v67, 0
	s_nop 1
	s_and_saveexec_b64 s[6:7], s[8:9]
	s_cbranch_execz .LBB0_130
	ds_read_b128 v[130:133], v84 offset:52224
	ds_read_b128 v[134:137], v84 offset:52288
	ds_read_b128 v[138:141], v84 offset:52352
	ds_read_b128 v[142:145], v84 offset:52416
	s_waitcnt vmcnt(0) lgkmcnt(3)
	v_mfma_f32_16x16x32_bf16 v[64:67], v[130:133], v[16:19], v[64:67]
	s_waitcnt lgkmcnt(2)
	v_mfma_f32_16x16x32_bf16 v[64:67], v[134:137], v[12:15], v[64:67]
	s_waitcnt lgkmcnt(1)
	v_mfma_f32_16x16x32_bf16 v[64:67], v[138:141], v[4:7], v[64:67]
	s_waitcnt lgkmcnt(0)
	v_mfma_f32_16x16x32_bf16 v[64:67], v[142:145], v[0:3], v[64:67]
.LBB0_130:
	s_or_b64 exec, exec, s[6:7]
	v_cmp_lt_i32_e32 vcc, 13, v85
	v_mov_b32 v68, 0
	v_mov_b32 v69, 0
	v_mov_b32 v70, 0
	v_mov_b32 v71, 0
	s_nop 1
	s_and_saveexec_b64 s[6:7], vcc
	s_cbranch_execz .LBB0_132
	ds_read_b128 v[146:149], v84 offset:56576
	ds_read_b128 v[150:153], v84 offset:56640
	ds_read_b128 v[154:157], v84 offset:56704
	ds_read_b128 v[158:161], v84 offset:56768
	s_waitcnt vmcnt(0) lgkmcnt(3)
	v_mfma_f32_16x16x32_bf16 v[68:71], v[146:149], v[16:19], v[68:71]
	s_waitcnt lgkmcnt(2)
	v_mfma_f32_16x16x32_bf16 v[68:71], v[150:153], v[12:15], v[68:71]
	s_waitcnt lgkmcnt(1)
	v_mfma_f32_16x16x32_bf16 v[68:71], v[154:157], v[4:7], v[68:71]
	s_waitcnt lgkmcnt(0)
	v_mfma_f32_16x16x32_bf16 v[68:71], v[158:161], v[0:3], v[68:71]
.LBB0_132:
	s_or_b64 exec, exec, s[6:7]
	v_cmp_lt_i32_e64 s[6:7], 14, v85
	v_mov_b32 v72, 0
	v_mov_b32 v73, 0
	v_mov_b32 v74, 0
	v_mov_b32 v75, 0
	s_nop 1
	s_and_saveexec_b64 s[24:25], s[6:7]
	s_cbranch_execz .LBB0_134
	ds_read_b128 v[130:133], v84 offset:60928
	ds_read_b128 v[134:137], v84 offset:60992
	ds_read_b128 v[138:141], v84 offset:61056
	ds_read_b128 v[142:145], v84 offset:61120
	s_waitcnt vmcnt(0) lgkmcnt(3)
	v_mfma_f32_16x16x32_bf16 v[72:75], v[130:133], v[16:19], v[72:75]
	s_waitcnt lgkmcnt(2)
	v_mfma_f32_16x16x32_bf16 v[72:75], v[134:137], v[12:15], v[72:75]
	s_waitcnt lgkmcnt(1)
	v_mfma_f32_16x16x32_bf16 v[72:75], v[138:141], v[4:7], v[72:75]
	s_waitcnt lgkmcnt(0)
	v_mfma_f32_16x16x32_bf16 v[72:75], v[142:145], v[0:3], v[72:75]

; DI void cmp_item(const Params& p, int item, LAS unsigned char* lds, int tid) {
;     ...
;     float mx = -1e30f;
; #pragma unroll
;     for (int a = 0; a < 16; ++a)
; #pragma unroll
;         for (int r = 0; r < 4; ++r) { const int n = a * 16 + quad * 4 + r; const float s = (n < nv) ? acc[a][r] * SC2 : -1e30f; acc[a][r] = s; mx = fmaxf(mx, s); }
.LBB0_136:
	s_or_b64 exec, exec, s[24:25]
	s_waitcnt vmcnt(0)
	v_bfe_u32 v12, v109, 4, 2
	s_waitcnt vmcnt(1)
	v_subrev_u32_e32 v0, 31, v82
	v_cmp_lt_i32_e32 vcc, 30, v82
	v_ashrrev_i32_e32 v0, 4, v0
	v_lshlrev_b32_e32 v82, 2, v12
	v_cmp_ge_i32_e64 s[24:25], v0, v82
	v_mul_f32_e32 v1, 0x3e0293ee, v8
	s_and_b64 s[24:25], vcc, s[24:25]
	v_cndmask_b32_e64 v1, v226, v1, s[24:25]
	v_cmp_gt_i32_e64 s[24:25], v0, v82
	v_mul_f32_e32 v2, 0x3e0293ee, v9
	s_and_b64 s[24:25], vcc, s[24:25]
	v_or_b32_e32 v4, 2, v82
	v_cndmask_b32_e64 v2, v226, v2, s[24:25]
	v_cmp_ge_i32_e64 s[24:25], v0, v4
	v_mul_f32_e32 v4, 0x3e0293ee, v10
	s_and_b64 s[24:25], vcc, s[24:25]
	v_or_b32_e32 v5, 3, v82
	v_cndmask_b32_e64 v4, v226, v4, s[24:25]
	v_cmp_ge_i32_e64 s[24:25], v0, v5
	v_mul_f32_e32 v5, 0x3e0293ee, v11
	s_and_b64 s[24:25], vcc, s[24:25]
	v_or_b32_e32 v6, 16, v82
	v_cndmask_b32_e64 v5, v226, v5, s[24:25]
	v_cmp_ge_i32_e64 s[24:25], v0, v6
	v_mul_f32_e32 v6, 0x3e0293ee, v20
	s_and_b64 s[24:25], vcc, s[24:25]
	v_or_b32_e32 v7, 17, v82
	v_cndmask_b32_e64 v6, v226, v6, s[24:25]
	v_cmp_ge_i32_e64 s[24:25], v0, v7
	v_mul_f32_e32 v7, 0x3e0293ee, v21
	s_and_b64 s[24:25], vcc, s[24:25]
	v_or_b32_e32 v8, 18, v82
	v_cndmask_b32_e64 v7, v226, v7, s[24:25]
	v_cmp_ge_i32_e64 s[24:25], v0, v8
	v_mul_f32_e32 v8, 0x3e0293ee, v22
	s_and_b64 s[24:25], vcc, s[24:25]
	v_or_b32_e32 v9, 19, v82
	v_cndmask_b32_e64 v8, v226, v8, s[24:25]
	v_cmp_ge_i32_e64 s[24:25], v0, v9
	v_mul_f32_e32 v9, 0x3e0293ee, v23
	s_and_b64 s[24:25], vcc, s[24:25]
	v_or_b32_e32 v10, 32, v82
	v_cndmask_b32_e64 v9, v226, v9, s[24:25]
	v_cmp_ge_i32_e64 s[24:25], v0, v10
	v_mul_f32_e32 v10, 0x3e0293ee, v24
	s_and_b64 s[24:25], vcc, s[24:25]
	v_or_b32_e32 v11, 33, v82
	v_cndmask_b32_e64 v10, v226, v10, s[24:25]
	v_cmp_ge_i32_e64 s[24:25], v0, v11
	v_mul_f32_e32 v11, 0x3e0293ee, v25
	s_and_b64 s[24:25], vcc, s[24:25]
	v_or_b32_e32 v13, 34, v82
	v_cndmask_b32_e64 v11, v226, v11, s[24:25]
	v_cmp_ge_i32_e64 s[24:25], v0, v13
	v_mul_f32_e32 v13, 0x3e0293ee, v26
	s_and_b64 s[24:25], vcc, s[24:25]
	v_or_b32_e32 v14, 35, v82
	v_cndmask_b32_e64 v13, v226, v13, s[24:25]
	v_cmp_ge_i32_e64 s[24:25], v0, v14
	v_mul_f32_e32 v14, 0x3e0293ee, v27
	s_and_b64 s[24:25], vcc, s[24:25]
	v_or_b32_e32 v15, 48, v82
	v_cndmask_b32_e64 v14, v226, v14, s[24:25]
	v_cmp_ge_i32_e64 s[24:25], v0, v15
	v_mul_f32_e32 v15, 0x3e0293ee, v28
	s_and_b64 s[24:25], vcc, s[24:25]
	v_or_b32_e32 v16, 49, v82
	v_cndmask_b32_e64 v15, v226, v15, s[24:25]
	v_cmp_ge_i32_e64 s[24:25], v0, v16
	v_mul_f32_e32 v16, 0x3e0293ee, v29
	s_and_b64 s[24:25], vcc, s[24:25]
	v_or_b32_e32 v17, 50, v82
	v_cndmask_b32_e64 v16, v226, v16, s[24:25]
	v_cmp_ge_i32_e64 s[24:25], v0, v17
	v_mul_f32_e32 v17, 0x3e0293ee, v30
	s_and_b64 s[24:25], vcc, s[24:25]
	v_or_b32_e32 v18, 51, v82
	v_cndmask_b32_e64 v17, v226, v17, s[24:25]
	v_cmp_ge_i32_e64 s[24:25], v0, v18
	v_mul_f32_e32 v18, 0x3e0293ee, v31
	s_and_b64 s[24:25], vcc, s[24:25]
	v_or_b32_e32 v19, 64, v82
	v_cndmask_b32_e64 v18, v226, v18, s[24:25]
	v_cmp_ge_i32_e64 s[24:25], v0, v19
	v_mul_f32_e32 v19, 0x3e0293ee, v32
	s_and_b64 s[24:25], vcc, s[24:25]
	v_or_b32_e32 v20, 0x41, v82
	v_cndmask_b32_e64 v19, v226, v19, s[24:25]
	v_cmp_ge_i32_e64 s[24:25], v0, v20
	v_mul_f32_e32 v20, 0x3e0293ee, v33
	s_and_b64 s[24:25], vcc, s[24:25]
	v_or_b32_e32 v21, 0x42, v82
	v_cndmask_b32_e64 v20, v226, v20, s[24:25]
	v_cmp_ge_i32_e64 s[24:25], v0, v21
	v_mul_f32_e32 v21, 0x3e0293ee, v34
	s_and_b64 s[24:25], vcc, s[24:25]
	v_or_b32_e32 v22, 0x43, v82
	v_cndmask_b32_e64 v21, v226, v21, s[24:25]
	v_cmp_ge_i32_e64 s[24:25], v0, v22
	v_mul_f32_e32 v22, 0x3e0293ee, v35
	s_and_b64 s[24:25], vcc, s[24:25]
	v_or_b32_e32 v23, 0x50, v82
	v_cndmask_b32_e64 v22, v226, v22, s[24:25]
	v_cmp_ge_i32_e64 s[24:25], v0, v23
	v_mul_f32_e32 v23, 0x3e0293ee, v36
	s_and_b64 s[24:25], vcc, s[24:25]
	v_or_b32_e32 v24, 0x51, v82
	v_cndmask_b32_e64 v23, v226, v23, s[24:25]
	v_cmp_ge_i32_e64 s[24:25], v0, v24
	v_mul_f32_e32 v24, 0x3e0293ee, v37
	s_and_b64 s[24:25], vcc, s[24:25]
	v_or_b32_e32 v25, 0x52, v82
	v_cndmask_b32_e64 v24, v226, v24, s[24:25]
	v_cmp_ge_i32_e64 s[24:25], v0, v25
	v_mul_f32_e32 v25, 0x3e0293ee, v38
	s_and_b64 s[24:25], vcc, s[24:25]
	v_or_b32_e32 v26, 0x53, v82
	v_cndmask_b32_e64 v25, v226, v25, s[24:25]
	v_cmp_ge_i32_e64 s[24:25], v0, v26
	v_mul_f32_e32 v26, 0x3e0293ee, v39
	s_and_b64 s[24:25], vcc, s[24:25]
	v_or_b32_e32 v27, 0x60, v82
	v_cndmask_b32_e64 v26, v226, v26, s[24:25]
	v_cmp_ge_i32_e64 s[24:25], v0, v27
	v_mul_f32_e32 v27, 0x3e0293ee, v40
	s_and_b64 s[24:25], vcc, s[24:25]
	v_or_b32_e32 v28, 0x61, v82
	v_cndmask_b32_e64 v27, v226, v27, s[24:25]
	v_cmp_ge_i32_e64 s[24:25], v0, v28
	v_mul_f32_e32 v28, 0x3e0293ee, v41
	s_and_b64 s[24:25], vcc, s[24:25]
	v_or_b32_e32 v29, 0x62, v82
	v_cndmask_b32_e64 v28, v226, v28, s[24:25]
	v_cmp_ge_i32_e64 s[24:25], v0, v29
	v_mul_f32_e32 v29, 0x3e0293ee, v42
	s_and_b64 s[24:25], vcc, s[24:25]
	v_or_b32_e32 v30, 0x63, v82
	v_cndmask_b32_e64 v29, v226, v29, s[24:25]
	v_cmp_ge_i32_e64 s[24:25], v0, v30
	v_mul_f32_e32 v30, 0x3e0293ee, v43
	s_and_b64 s[24:25], vcc, s[24:25]
	v_or_b32_e32 v31, 0x70, v82
	v_cndmask_b32_e64 v30, v226, v30, s[24:25]
	v_cmp_ge_i32_e64 s[24:25], v0, v31
	v_mul_f32_e32 v31, 0x3e0293ee, v44
	s_and_b64 s[24:25], vcc, s[24:25]
	v_or_b32_e32 v32, 0x71, v82
	v_cndmask_b32_e64 v31, v226, v31, s[24:25]
	v_cmp_ge_i32_e64 s[24:25], v0, v32
	v_mul_f32_e32 v32, 0x3e0293ee, v45
	s_and_b64 s[24:25], vcc, s[24:25]
	v_or_b32_e32 v33, 0x72, v82
	v_cndmask_b32_e64 v32, v226, v32, s[24:25]
	v_cmp_ge_i32_e64 s[24:25], v0, v33
	v_mul_f32_e32 v33, 0x3e0293ee, v46
	s_and_b64 s[24:25], vcc, s[24:25]
; DI void cmp_item(const Params& p, int item, LAS unsigned char* lds, int tid) {
;     ...
;     float mx = -1e30f;
; #pragma unroll
;     for (int a = 0; a < 16; ++a)
; #pragma unroll
;         for (int r = 0; r < 4; ++r) { const int n = a * 16 + quad * 4 + r; const float s = (n < nv) ? acc[a][r] * SC2 : -1e30f; acc[a][r] = s; mx = fmaxf(mx, s); }
;     mx = xq_max(mx);
	v_or_b32_e32 v34, 0x73, v82
	v_cndmask_b32_e64 v33, v226, v33, s[24:25]
	v_cmp_ge_i32_e64 s[24:25], v0, v34
	v_mul_f32_e32 v34, 0x3e0293ee, v47
	s_and_b64 s[24:25], vcc, s[24:25]
	v_or_b32_e32 v35, 0x80, v82
	v_cndmask_b32_e64 v34, v226, v34, s[24:25]
	v_cmp_ge_i32_e64 s[24:25], v0, v35
	v_mul_f32_e32 v35, 0x3e0293ee, v48
	s_and_b64 s[24:25], vcc, s[24:25]
	v_or_b32_e32 v36, 0x81, v82
	v_cndmask_b32_e64 v35, v226, v35, s[24:25]
	v_cmp_ge_i32_e64 s[24:25], v0, v36
	v_mul_f32_e32 v36, 0x3e0293ee, v49
	s_and_b64 s[24:25], vcc, s[24:25]
	v_or_b32_e32 v37, 0x82, v82
	v_cndmask_b32_e64 v36, v226, v36, s[24:25]
	v_cmp_ge_i32_e64 s[24:25], v0, v37
	v_mul_f32_e32 v37, 0x3e0293ee, v50
	s_and_b64 s[24:25], vcc, s[24:25]
	v_or_b32_e32 v38, 0x83, v82
	v_cndmask_b32_e64 v37, v226, v37, s[24:25]
	v_cmp_ge_i32_e64 s[24:25], v0, v38
	v_mul_f32_e32 v38, 0x3e0293ee, v51
	s_and_b64 s[24:25], vcc, s[24:25]
	v_or_b32_e32 v39, 0x90, v82
	v_cndmask_b32_e64 v38, v226, v38, s[24:25]
	v_cmp_ge_i32_e64 s[24:25], v0, v39
	v_mul_f32_e32 v39, 0x3e0293ee, v52
	s_and_b64 s[24:25], vcc, s[24:25]
	v_or_b32_e32 v40, 0x91, v82
	v_cndmask_b32_e64 v39, v226, v39, s[24:25]
	v_cmp_ge_i32_e64 s[24:25], v0, v40
	v_mul_f32_e32 v40, 0x3e0293ee, v53
	s_and_b64 s[24:25], vcc, s[24:25]
	v_cndmask_b32_e64 v44, v226, v40, s[24:25]
	v_or_b32_e32 v40, 0x92, v82
	v_cmp_ge_i32_e64 s[24:25], v0, v40
	v_mul_f32_e32 v40, 0x3e0293ee, v54
	s_and_b64 s[24:25], vcc, s[24:25]
	v_cndmask_b32_e64 v45, v226, v40, s[24:25]
	v_or_b32_e32 v40, 0x93, v82
	v_cmp_ge_i32_e64 s[24:25], v0, v40
	v_mul_f32_e32 v40, 0x3e0293ee, v55
	s_and_b64 s[24:25], vcc, s[24:25]
	v_cndmask_b32_e64 v46, v226, v40, s[24:25]
	v_or_b32_e32 v40, 0xa0, v82
	v_cmp_ge_i32_e64 s[24:25], v0, v40
	v_mul_f32_e32 v40, 0x3e0293ee, v56
	s_and_b64 s[24:25], vcc, s[24:25]
	v_cndmask_b32_e64 v47, v226, v40, s[24:25]
	v_or_b32_e32 v40, 0xa1, v82
	v_cmp_ge_i32_e64 s[24:25], v0, v40
	v_mul_f32_e32 v40, 0x3e0293ee, v57
	s_and_b64 s[24:25], vcc, s[24:25]
	v_cndmask_b32_e64 v48, v226, v40, s[24:25]
	v_or_b32_e32 v40, 0xa2, v82
	v_cmp_ge_i32_e64 s[24:25], v0, v40
	v_mul_f32_e32 v40, 0x3e0293ee, v58
	s_and_b64 s[24:25], vcc, s[24:25]
	v_cndmask_b32_e64 v49, v226, v40, s[24:25]
	v_or_b32_e32 v40, 0xa3, v82
	v_cmp_ge_i32_e64 s[24:25], v0, v40
	v_mul_f32_e32 v40, 0x3e0293ee, v59
	s_and_b64 s[24:25], vcc, s[24:25]
	v_cndmask_b32_e64 v50, v226, v40, s[24:25]
	v_or_b32_e32 v40, 0xb0, v82
	v_cmp_ge_i32_e64 s[24:25], v0, v40
	v_mul_f32_e32 v40, 0x3e0293ee, v60
	s_and_b64 s[24:25], vcc, s[24:25]
	v_cndmask_b32_e64 v51, v226, v40, s[24:25]
	v_or_b32_e32 v40, 0xb1, v82
	v_cmp_ge_i32_e64 s[24:25], v0, v40
	v_mul_f32_e32 v40, 0x3e0293ee, v61
	s_and_b64 s[24:25], vcc, s[24:25]
	v_cndmask_b32_e64 v52, v226, v40, s[24:25]
	v_or_b32_e32 v40, 0xb2, v82
	v_cmp_ge_i32_e64 s[24:25], v0, v40
	v_mul_f32_e32 v40, 0x3e0293ee, v62
	s_and_b64 s[24:25], vcc, s[24:25]
	v_cndmask_b32_e64 v53, v226, v40, s[24:25]
	v_or_b32_e32 v40, 0xb3, v82
	v_cmp_ge_i32_e64 s[24:25], v0, v40
	v_mul_f32_e32 v40, 0x3e0293ee, v63
	s_and_b64 s[24:25], vcc, s[24:25]
	v_cndmask_b32_e64 v54, v226, v40, s[24:25]
	v_or_b32_e32 v40, 0xc0, v82
	v_cmp_ge_i32_e64 s[24:25], v0, v40
	v_mul_f32_e32 v40, 0x3e0293ee, v64
	s_and_b64 s[24:25], vcc, s[24:25]
	v_cndmask_b32_e64 v55, v226, v40, s[24:25]
	v_or_b32_e32 v40, 0xc1, v82
	v_cmp_ge_i32_e64 s[24:25], v0, v40
	v_mul_f32_e32 v40, 0x3e0293ee, v65
	s_and_b64 s[24:25], vcc, s[24:25]
	v_cndmask_b32_e64 v61, v226, v40, s[24:25]
	v_or_b32_e32 v40, 0xc2, v82
	v_cmp_ge_i32_e64 s[24:25], v0, v40
	v_mul_f32_e32 v40, 0x3e0293ee, v66
	s_and_b64 s[24:25], vcc, s[24:25]
	v_cndmask_b32_e64 v62, v226, v40, s[24:25]
	v_or_b32_e32 v40, 0xc3, v82
	v_cmp_ge_i32_e64 s[24:25], v0, v40
	v_mul_f32_e32 v40, 0x3e0293ee, v67
	s_and_b64 s[24:25], vcc, s[24:25]
	v_cndmask_b32_e64 v63, v226, v40, s[24:25]
	v_or_b32_e32 v40, 0xd0, v82
	v_cmp_ge_i32_e64 s[24:25], v0, v40
	v_mul_f32_e32 v40, 0x3e0293ee, v68
	s_and_b64 s[24:25], vcc, s[24:25]
	v_cndmask_b32_e64 v107, v226, v40, s[24:25]
	v_or_b32_e32 v40, 0xd1, v82
	v_cmp_ge_i32_e64 s[24:25], v0, v40
	v_mul_f32_e32 v40, 0x3e0293ee, v69
	s_and_b64 s[24:25], vcc, s[24:25]
	v_max3_f32 v3, v1, s97, v2
	v_cndmask_b32_e64 v113, v226, v40, s[24:25]
	v_or_b32_e32 v40, 0xd2, v82
	v_max3_f32 v3, v3, v4, v5
	v_cmp_ge_i32_e64 s[24:25], v0, v40
	v_max3_f32 v3, v3, v6, v7
	v_mul_f32_e32 v40, 0x3e0293ee, v70
	s_and_b64 s[24:25], vcc, s[24:25]
	v_max3_f32 v3, v3, v8, v9
	v_cndmask_b32_e64 v114, v226, v40, s[24:25]
	v_or_b32_e32 v40, 0xd3, v82
	v_max3_f32 v3, v3, v10, v11
	v_cmp_ge_i32_e64 s[24:25], v0, v40
	v_max3_f32 v3, v3, v13, v14
	v_mul_f32_e32 v40, 0x3e0293ee, v71
	s_and_b64 s[24:25], vcc, s[24:25]
	v_max3_f32 v3, v3, v15, v16
	v_cndmask_b32_e64 v115, v226, v40, s[24:25]
	v_or_b32_e32 v40, 0xe0, v82
	v_max3_f32 v3, v3, v17, v18
	v_cmp_ge_i32_e64 s[24:25], v0, v40
	v_max3_f32 v3, v3, v19, v20
	v_mul_f32_e32 v40, 0x3e0293ee, v72
	s_and_b64 s[24:25], vcc, s[24:25]
	v_max3_f32 v3, v3, v21, v22
	v_cndmask_b32_e64 v116, v226, v40, s[24:25]
	v_or_b32_e32 v40, 0xe1, v82
	v_max3_f32 v3, v3, v23, v24
	v_cmp_ge_i32_e64 s[24:25], v0, v40
	v_max3_f32 v3, v3, v25, v26
	v_mul_f32_e32 v40, 0x3e0293ee, v73
	s_and_b64 s[24:25], vcc, s[24:25]
	v_max3_f32 v3, v3, v27, v28
	v_cndmask_b32_e64 v117, v226, v40, s[24:25]
	v_or_b32_e32 v40, 0xe2, v82
	v_max3_f32 v3, v3, v29, v30
	v_cmp_ge_i32_e64 s[24:25], v0, v40
	v_max3_f32 v3, v3, v31, v32
	v_mul_f32_e32 v40, 0x3e0293ee, v74
	s_and_b64 s[24:25], vcc, s[24:25]
	v_max3_f32 v3, v3, v33, v34
	v_cndmask_b32_e64 v118, v226, v40, s[24:25]
	v_or_b32_e32 v40, 0xe3, v82
	v_max3_f32 v3, v3, v35, v36
	v_cmp_ge_i32_e64 s[24:25], v0, v40
; DI void cmp_item(const Params& p, int item, LAS unsigned char* lds, int tid) {
;     ...
;         for (int r = 0; r < 4; ++r) { const int n = a * 16 + quad * 4 + r; const float s = (n < nv) ? acc[a][r] * SC2 : -1e30f; acc[a][r] = s; mx = fmaxf(mx, s); }
;     mx = xq_max(mx);
;     float sum = 0.f;
; #pragma unroll
;     for (int a = 0; a < 16; ++a)
; #pragma unroll
;         for (int r = 0; r < 4; ++r) { const float pe = (acc[a][r] > -1e29f) ? __builtin_amdgcn_exp2f(acc[a][r] - mx) : 0.f; acc[a][r] = pe; sum += pe; }
;     sum = xq_sum(sum);
	v_max3_f32 v3, v3, v37, v38
	v_mul_f32_e32 v40, 0x3e0293ee, v75
	s_and_b64 s[24:25], vcc, s[24:25]
	v_max3_f32 v3, v3, v39, v44
	v_cndmask_b32_e64 v119, v226, v40, s[24:25]
	v_or_b32_e32 v40, 0xf0, v82
	v_max3_f32 v3, v3, v45, v46
	v_cmp_ge_i32_e64 s[24:25], v0, v40
	v_max3_f32 v3, v3, v47, v48
	v_mul_f32_e32 v40, 0x3e0293ee, v76
	s_and_b64 s[24:25], vcc, s[24:25]
	v_max3_f32 v3, v3, v49, v50
	v_cndmask_b32_e64 v120, v226, v40, s[24:25]
	v_or_b32_e32 v40, 0xf1, v82
	v_max3_f32 v3, v3, v51, v52
	v_cmp_ge_i32_e64 s[24:25], v0, v40
	v_max3_f32 v3, v3, v53, v54
	v_mul_f32_e32 v40, 0x3e0293ee, v77
	s_and_b64 s[24:25], vcc, s[24:25]
	v_max3_f32 v3, v3, v55, v61
	v_cndmask_b32_e64 v121, v226, v40, s[24:25]
	v_or_b32_e32 v40, 0xf2, v82
	v_max3_f32 v3, v3, v62, v63
	v_cmp_ge_i32_e64 s[24:25], v0, v40
	v_max3_f32 v3, v3, v107, v113
	v_mul_f32_e32 v40, 0x3e0293ee, v78
	s_and_b64 s[24:25], vcc, s[24:25]
	v_max3_f32 v3, v3, v114, v115
	v_cndmask_b32_e64 v122, v226, v40, s[24:25]
	v_or_b32_e32 v40, 0xf3, v82
	v_max3_f32 v3, v3, v116, v117
	v_cmp_ge_i32_e64 s[24:25], v0, v40
	v_max3_f32 v3, v3, v118, v119
	v_mul_f32_e32 v0, 0x3e0293ee, v79
	s_and_b64 vcc, vcc, s[24:25]
	v_max3_f32 v3, v3, v120, v121
	v_cndmask_b32_e32 v123, v226, v0, vcc
	v_max3_f32 v0, v3, v122, v123
	v_mov_b32_e32 v3, v0
	s_nop 1
	v_permlane16_swap_b32_e32 v0, v3
	v_max_f32_e32 v3, v3, v3
	v_max_f32_e32 v0, v0, v0
	v_max_f32_e32 v0, v0, v3
	v_mov_b32_e32 v3, v0
	s_nop 1
	v_permlane32_swap_b32_e32 v0, v3
	v_max_f32_e32 v3, v3, v3
	v_max_f32_e32 v0, v0, v0
	v_max_f32_e32 v124, v0, v3
	v_sub_f32_e32 v0, v1, v124
	v_exp_f32_e32 v0, v0
	v_sub_f32_e32 v3, v2, v124
	v_exp_f32_e32 v3, v3
	v_cmp_lt_f32_e32 vcc, s40, v1
	s_nop 1
	v_cndmask_b32_e32 v0, 0, v0, vcc
	v_cmp_lt_f32_e32 vcc, s40, v2
	v_add_f32_e32 v40, 0, v0
	v_sub_f32_e32 v2, v4, v124
	v_cndmask_b32_e32 v1, 0, v3, vcc
	v_add_f32_e32 v3, v1, v40
	v_exp_f32_e32 v2, v2
	v_sub_f32_e32 v40, v5, v124
	v_exp_f32_e32 v40, v40
	v_cmp_lt_f32_e32 vcc, s40, v4
	s_nop 1
	v_cndmask_b32_e32 v2, 0, v2, vcc
	v_cmp_lt_f32_e32 vcc, s40, v5
	v_add_f32_e32 v4, v2, v3
	s_nop 0
	v_cndmask_b32_e32 v3, 0, v40, vcc
	v_add_f32_e32 v5, v3, v4
	v_sub_f32_e32 v4, v6, v124
	v_exp_f32_e32 v4, v4
	v_sub_f32_e32 v40, v7, v124
	v_exp_f32_e32 v40, v40
	v_cmp_lt_f32_e32 vcc, s40, v6
	s_nop 1
	v_cndmask_b32_e32 v4, 0, v4, vcc
	v_cmp_lt_f32_e32 vcc, s40, v7
	v_add_f32_e32 v6, v4, v5
	s_nop 0
	v_cndmask_b32_e32 v5, 0, v40, vcc
	v_add_f32_e32 v7, v5, v6
	v_sub_f32_e32 v6, v8, v124
	v_exp_f32_e32 v6, v6
	v_sub_f32_e32 v40, v9, v124
	v_cmp_lt_f32_e32 vcc, s40, v8
	v_exp_f32_e32 v40, v40
	s_nop 0
	v_cndmask_b32_e32 v6, 0, v6, vcc
	v_cmp_lt_f32_e32 vcc, s40, v9
	v_sub_f32_e32 v9, v10, v124
	v_exp_f32_e32 v9, v9
	v_add_f32_e32 v8, v6, v7
	v_cndmask_b32_e32 v7, 0, v40, vcc
	v_sub_f32_e32 v40, v11, v124
	v_cmp_lt_f32_e32 vcc, s40, v10
	v_exp_f32_e32 v41, v40
	v_sub_f32_e32 v10, v14, v124
	v_cndmask_b32_e32 v40, 0, v9, vcc
	v_sub_f32_e32 v9, v13, v124
	v_exp_f32_e32 v9, v9
	v_exp_f32_e32 v10, v10
	v_cmp_lt_f32_e32 vcc, s40, v11
	v_add_f32_e32 v8, v7, v8
	v_add_f32_e32 v8, v40, v8
	v_cndmask_b32_e32 v41, 0, v41, vcc
	v_cmp_lt_f32_e32 vcc, s40, v13
	v_add_f32_e32 v8, v41, v8
	s_nop 0
	v_cndmask_b32_e32 v42, 0, v9, vcc
	v_cmp_lt_f32_e32 vcc, s40, v14
	v_sub_f32_e32 v9, v15, v124
	v_exp_f32_e32 v9, v9
	v_cndmask_b32_e32 v43, 0, v10, vcc
	v_sub_f32_e32 v10, v16, v124
	v_exp_f32_e32 v10, v10
	v_cmp_lt_f32_e32 vcc, s40, v15
	v_add_f32_e32 v8, v42, v8
	v_add_f32_e32 v8, v43, v8
	v_cndmask_b32_e32 v64, 0, v9, vcc
	v_cmp_lt_f32_e32 vcc, s40, v16
	v_sub_f32_e32 v9, v17, v124
	v_exp_f32_e32 v9, v9
	v_cndmask_b32_e32 v65, 0, v10, vcc
	v_sub_f32_e32 v10, v18, v124
	v_exp_f32_e32 v10, v10
	v_cmp_lt_f32_e32 vcc, s40, v17
	v_add_f32_e32 v8, v64, v8
	v_add_f32_e32 v8, v65, v8
	v_cndmask_b32_e32 v66, 0, v9, vcc
	v_cmp_lt_f32_e32 vcc, s40, v18
	v_sub_f32_e32 v9, v19, v124
	v_exp_f32_e32 v9, v9
	v_cndmask_b32_e32 v67, 0, v10, vcc
	v_sub_f32_e32 v10, v20, v124
	v_exp_f32_e32 v10, v10
	v_cmp_lt_f32_e32 vcc, s40, v19
	v_add_f32_e32 v8, v66, v8
	v_add_f32_e32 v8, v67, v8
	v_cndmask_b32_e32 v56, 0, v9, vcc
	v_cmp_lt_f32_e32 vcc, s40, v20
	v_sub_f32_e32 v9, v21, v124
	v_exp_f32_e32 v9, v9
	v_cndmask_b32_e32 v57, 0, v10, vcc
	v_sub_f32_e32 v10, v22, v124
	v_exp_f32_e32 v10, v10
	v_cmp_lt_f32_e32 vcc, s40, v21
	v_add_f32_e32 v8, v56, v8
	v_add_f32_e32 v8, v57, v8
	v_cndmask_b32_e32 v58, 0, v9, vcc
	v_cmp_lt_f32_e32 vcc, s40, v22
	v_sub_f32_e32 v9, v23, v124
	v_exp_f32_e32 v9, v9
	v_cndmask_b32_e32 v59, 0, v10, vcc
	v_sub_f32_e32 v10, v24, v124
	v_exp_f32_e32 v10, v10
	v_cmp_lt_f32_e32 vcc, s40, v23
	v_add_f32_e32 v8, v58, v8
	v_add_f32_e32 v8, v59, v8
	v_cndmask_b32_e32 v86, 0, v9, vcc
	v_cmp_lt_f32_e32 vcc, s40, v24
	v_sub_f32_e32 v9, v25, v124
	v_exp_f32_e32 v9, v9
	v_cndmask_b32_e32 v87, 0, v10, vcc
	v_sub_f32_e32 v10, v26, v124
	v_exp_f32_e32 v10, v10
	v_cmp_lt_f32_e32 vcc, s40, v25
	v_add_f32_e32 v8, v86, v8
	v_add_f32_e32 v8, v87, v8
	v_cndmask_b32_e32 v90, 0, v9, vcc
	v_cmp_lt_f32_e32 vcc, s40, v26
	v_sub_f32_e32 v9, v27, v124
	v_exp_f32_e32 v9, v9
	v_cndmask_b32_e32 v91, 0, v10, vcc
	v_sub_f32_e32 v10, v28, v124
	v_exp_f32_e32 v10, v10
	v_cmp_lt_f32_e32 vcc, s40, v27
	v_add_f32_e32 v8, v90, v8
	v_add_f32_e32 v8, v91, v8
	v_cndmask_b32_e32 v76, 0, v9, vcc
	v_cmp_lt_f32_e32 vcc, s40, v28
	v_sub_f32_e32 v9, v29, v124
	v_exp_f32_e32 v9, v9
	v_cndmask_b32_e32 v77, 0, v10, vcc
	v_sub_f32_e32 v10, v30, v124
	v_exp_f32_e32 v10, v10
	v_cmp_lt_f32_e32 vcc, s40, v29
	v_add_f32_e32 v8, v76, v8
	v_add_f32_e32 v8, v77, v8
	v_cndmask_b32_e32 v78, 0, v9, vcc
	v_cmp_lt_f32_e32 vcc, s40, v30
	v_sub_f32_e32 v9, v31, v124
; DI f32x4 zero4() { float a, b, c, d; asm volatile("v_mov_b32 %0, 0\n\tv_mov_b32 %1, 0\n\tv_mov_b32 %2, 0\n\tv_mov_b32 %3, 0\n\ts_nop 1" : "=v"(a), "=v"(b), "=v"(c), "=v"(d)); return (f32x4){a, b, c, d}; }
; DI void cmp_item(const Params& p, int item, LAS unsigned char* lds, int tid) {
;     ...
;     for (int a = 0; a < 16; ++a)
; #pragma unroll
;         for (int r = 0; r < 4; ++r) { const float pe = (acc[a][r] > -1e29f) ? __builtin_amdgcn_exp2f(acc[a][r] - mx) : 0.f; acc[a][r] = pe; sum += pe; }
;     sum = xq_sum(sum);
;     const float inv = (sum > 0.f) ? 1.f / sum : 0.f;
; #pragma unroll
;     for (int a = 0; a < 16; ++a) acc[a] *= inv;
;     f32x4 O[8];
; #pragma unroll
;     for (int dt = 0; dt < 8; ++dt) O[dt] = zero4();
	v_exp_f32_e32 v9, v9
	v_cndmask_b32_e32 v79, 0, v10, vcc
	v_sub_f32_e32 v10, v32, v124
	v_exp_f32_e32 v10, v10
	v_cmp_lt_f32_e32 vcc, s40, v31
	v_add_f32_e32 v8, v78, v8
	v_add_f32_e32 v8, v79, v8
	v_cndmask_b32_e32 v100, 0, v9, vcc
	v_cmp_lt_f32_e32 vcc, s40, v32
	v_sub_f32_e32 v9, v33, v124
	v_exp_f32_e32 v9, v9
	v_cndmask_b32_e32 v101, 0, v10, vcc
	v_sub_f32_e32 v10, v34, v124
	v_exp_f32_e32 v10, v10
	v_cmp_lt_f32_e32 vcc, s40, v33
	v_add_f32_e32 v8, v100, v8
	v_add_f32_e32 v8, v101, v8
	v_cndmask_b32_e32 v104, 0, v9, vcc
	v_cmp_lt_f32_e32 vcc, s40, v34
	v_sub_f32_e32 v9, v35, v124
	v_exp_f32_e32 v9, v9
	v_cndmask_b32_e32 v105, 0, v10, vcc
	v_sub_f32_e32 v10, v36, v124
	v_exp_f32_e32 v10, v10
	v_cmp_lt_f32_e32 vcc, s40, v35
	v_add_f32_e32 v8, v104, v8
	v_add_f32_e32 v8, v105, v8
	v_cndmask_b32_e32 v94, 0, v9, vcc
	v_cmp_lt_f32_e32 vcc, s40, v36
	v_sub_f32_e32 v9, v37, v124
	v_exp_f32_e32 v9, v9
	v_cndmask_b32_e32 v95, 0, v10, vcc
	v_sub_f32_e32 v10, v38, v124
	v_exp_f32_e32 v10, v10
	v_cmp_lt_f32_e32 vcc, s40, v37
	v_add_f32_e32 v8, v94, v8
	v_add_f32_e32 v8, v95, v8
	v_cndmask_b32_e32 v96, 0, v9, vcc
	v_cmp_lt_f32_e32 vcc, s40, v38
	v_sub_f32_e32 v9, v39, v124
	v_exp_f32_e32 v9, v9
	v_cndmask_b32_e32 v97, 0, v10, vcc
	v_sub_f32_e32 v10, v44, v124
	v_exp_f32_e32 v10, v10
	v_cmp_lt_f32_e32 vcc, s40, v39
	v_add_f32_e32 v8, v96, v8
	v_add_f32_e32 v8, v97, v8
	v_cndmask_b32_e32 v98, 0, v9, vcc
	v_cmp_lt_f32_e32 vcc, s40, v44
	v_sub_f32_e32 v9, v45, v124
	v_exp_f32_e32 v9, v9
	v_cndmask_b32_e32 v99, 0, v10, vcc
	v_sub_f32_e32 v10, v46, v124
	v_exp_f32_e32 v10, v10
	v_cmp_lt_f32_e32 vcc, s40, v45
	v_add_f32_e32 v8, v98, v8
	v_add_f32_e32 v8, v99, v8
	v_cndmask_b32_e32 v102, 0, v9, vcc
	v_cmp_lt_f32_e32 vcc, s40, v46
	v_sub_f32_e32 v9, v47, v124
	v_exp_f32_e32 v9, v9
	v_cndmask_b32_e32 v103, 0, v10, vcc
	v_sub_f32_e32 v10, v48, v124
	v_exp_f32_e32 v10, v10
	v_cmp_lt_f32_e32 vcc, s40, v47
	v_add_f32_e32 v8, v102, v8
	v_add_f32_e32 v8, v103, v8
	v_cndmask_b32_e32 v74, 0, v9, vcc
	v_cmp_lt_f32_e32 vcc, s40, v48
	v_sub_f32_e32 v9, v49, v124
	v_exp_f32_e32 v9, v9
	v_cndmask_b32_e32 v75, 0, v10, vcc
	v_sub_f32_e32 v10, v50, v124
	v_exp_f32_e32 v10, v10
	v_cmp_lt_f32_e32 vcc, s40, v49
	v_add_f32_e32 v8, v74, v8
	v_add_f32_e32 v8, v75, v8
	v_cndmask_b32_e32 v84, 0, v9, vcc
	v_cmp_lt_f32_e32 vcc, s40, v50
	v_sub_f32_e32 v9, v51, v124
	v_exp_f32_e32 v9, v9
	v_cndmask_b32_e32 v85, 0, v10, vcc
	v_sub_f32_e32 v10, v52, v124
	v_exp_f32_e32 v10, v10
	v_cmp_lt_f32_e32 vcc, s40, v51
	v_add_f32_e32 v8, v84, v8
	v_add_f32_e32 v8, v85, v8
	v_cndmask_b32_e32 v88, 0, v9, vcc
	v_cmp_lt_f32_e32 vcc, s40, v52
	v_sub_f32_e32 v9, v53, v124
	v_exp_f32_e32 v9, v9
	v_cndmask_b32_e32 v89, 0, v10, vcc
	v_sub_f32_e32 v10, v54, v124
	v_exp_f32_e32 v10, v10
	v_cmp_lt_f32_e32 vcc, s40, v53
	v_add_f32_e32 v8, v88, v8
	v_add_f32_e32 v8, v89, v8
	v_cndmask_b32_e32 v92, 0, v9, vcc
	v_cmp_lt_f32_e32 vcc, s40, v54
	v_sub_f32_e32 v9, v55, v124
	v_exp_f32_e32 v9, v9
	v_cndmask_b32_e32 v93, 0, v10, vcc
	v_sub_f32_e32 v10, v61, v124
	v_exp_f32_e32 v10, v10
	v_cmp_lt_f32_e32 vcc, s40, v55
	v_add_f32_e32 v8, v92, v8
	v_add_f32_e32 v8, v93, v8
	v_cndmask_b32_e32 v60, 0, v9, vcc
	v_cmp_lt_f32_e32 vcc, s40, v61
	v_sub_f32_e32 v9, v62, v124
	v_exp_f32_e32 v9, v9
	v_cndmask_b32_e32 v61, 0, v10, vcc
	v_sub_f32_e32 v10, v63, v124
	v_exp_f32_e32 v10, v10
	v_cmp_lt_f32_e32 vcc, s40, v62
	v_add_f32_e32 v8, v60, v8
	v_add_f32_e32 v8, v61, v8
	v_cndmask_b32_e32 v68, 0, v9, vcc
	v_cmp_lt_f32_e32 vcc, s40, v63
	v_sub_f32_e32 v9, v107, v124
	v_exp_f32_e32 v9, v9
	v_cndmask_b32_e32 v69, 0, v10, vcc
	v_sub_f32_e32 v10, v113, v124
	v_exp_f32_e32 v10, v10
	v_cmp_lt_f32_e32 vcc, s40, v107
	v_add_f32_e32 v8, v68, v8
	v_add_f32_e32 v8, v69, v8
	v_cndmask_b32_e32 v70, 0, v9, vcc
	v_cmp_lt_f32_e32 vcc, s40, v113
	v_sub_f32_e32 v9, v114, v124
	v_exp_f32_e32 v9, v9
	v_cndmask_b32_e32 v71, 0, v10, vcc
	v_sub_f32_e32 v10, v115, v124
	v_exp_f32_e32 v10, v10
	v_cmp_lt_f32_e32 vcc, s40, v114
	v_add_f32_e32 v8, v70, v8
	v_add_f32_e32 v8, v71, v8
	v_cndmask_b32_e32 v72, 0, v9, vcc
	v_cmp_lt_f32_e32 vcc, s40, v115
	v_sub_f32_e32 v9, v116, v124
	v_exp_f32_e32 v9, v9
	v_cndmask_b32_e32 v73, 0, v10, vcc
	v_sub_f32_e32 v10, v117, v124
	v_exp_f32_e32 v10, v10
	v_cmp_lt_f32_e32 vcc, s40, v116
	v_add_f32_e32 v8, v72, v8
	v_add_f32_e32 v8, v73, v8
	v_cndmask_b32_e32 v48, 0, v9, vcc
	v_cmp_lt_f32_e32 vcc, s40, v117
	v_sub_f32_e32 v9, v118, v124
	v_exp_f32_e32 v9, v9
	v_cndmask_b32_e32 v49, 0, v10, vcc
	v_sub_f32_e32 v10, v119, v124
	v_exp_f32_e32 v10, v10
	v_cmp_lt_f32_e32 vcc, s40, v118
	v_add_f32_e32 v8, v48, v8
	v_add_f32_e32 v8, v49, v8
	v_cndmask_b32_e32 v50, 0, v9, vcc
	v_cmp_lt_f32_e32 vcc, s40, v119
	v_sub_f32_e32 v9, v120, v124
	v_exp_f32_e32 v9, v9
	v_cndmask_b32_e32 v51, 0, v10, vcc
	v_sub_f32_e32 v10, v121, v124
	v_exp_f32_e32 v10, v10
	v_cmp_lt_f32_e32 vcc, s40, v120
	v_add_f32_e32 v8, v50, v8
	v_add_f32_e32 v8, v51, v8
	v_cndmask_b32_e32 v52, 0, v9, vcc
	v_cmp_lt_f32_e32 vcc, s40, v121
	v_sub_f32_e32 v9, v122, v124
	v_exp_f32_e32 v9, v9
	v_cndmask_b32_e32 v53, 0, v10, vcc
	v_sub_f32_e32 v10, v123, v124
	v_exp_f32_e32 v10, v10
	v_add_f32_e32 v8, v52, v8
	v_cmp_lt_f32_e32 vcc, s40, v122
	v_add_f32_e32 v8, v53, v8
	v_lshlrev_b32_e32 v44, 3, v12
	v_cndmask_b32_e32 v54, 0, v9, vcc
	v_cmp_lt_f32_e32 vcc, s40, v123
	v_add_f32_e32 v8, v54, v8
	v_mov_b32 v28, 0
	v_mov_b32 v29, 0
	v_mov_b32 v30, 0
	v_mov_b32 v31, 0
	s_nop 1
	v_mov_b32 v24, 0
	v_mov_b32 v25, 0
	v_mov_b32 v26, 0
	v_mov_b32 v27, 0
	s_nop 1
	v_mov_b32 v20, 0
	v_mov_b32 v21, 0
	v_mov_b32 v22, 0
	v_mov_b32 v23, 0
	s_nop 1
	v_mov_b32 v16, 0
	v_mov_b32 v17, 0
; #define LAS __attribute__((address_space(3)))
; DI f32x4 zero4() { float a, b, c, d; asm volatile("v_mov_b32 %0, 0\n\tv_mov_b32 %1, 0\n\tv_mov_b32 %2, 0\n\tv_mov_b32 %3, 0\n\ts_nop 1" : "=v"(a), "=v"(b), "=v"(c), "=v"(d)); return (f32x4){a, b, c, d}; }
; DI unsigned pk2(float lo, float hi) { f32x2 v = {lo, hi}; bf16v2 b = __builtin_convertvector(v, bf16v2); return __builtin_bit_cast(unsigned, b); }
; DI void cmp_item(const Params& p, int item, LAS unsigned char* lds, int tid) {
;     ...
;     sum = xq_sum(sum);
;     const float inv = (sum > 0.f) ? 1.f / sum : 0.f;
; #pragma unroll
;     for (int a = 0; a < 16; ++a) acc[a] *= inv;
;     f32x4 O[8];
; #pragma unroll
;     for (int dt = 0; dt < 8; ++dt) O[dt] = zero4();
; #pragma unroll
;     for (int k2 = 0; k2 < 8; ++k2) {
;         if (2 * k2 < ntile) {
;             u32x4 pa; pa.x = pk2(acc[2 * k2][0], acc[2 * k2][1]); pa.y = pk2(acc[2 * k2][2], acc[2 * k2][3]); pa.z = pk2(acc[2 * k2 + 1][0], acc[2 * k2 + 1][1]); pa.w = pk2(acc[2 * k2 + 1][2], acc[2 * k2 + 1][3]);
;             const bf16x8 pv = __builtin_bit_cast(bf16x8, pa);
; #pragma unroll
;             for (int dt = 0; dt < 8; ++dt) { const LAS bf16_t* vp = vcL + (dt * 16 + i16) * 264 + k2 * 32 + quad * 4;
;                 const u32x2 lo = *(const LAS u32x2*)vp, hi = *(const LAS u32x2*)(vp + 16);
;                 const bf16x8 vv = __builtin_bit_cast(bf16x8, (u32x4){lo.x, lo.y, hi.x, hi.y});
;                 O[dt] = __builtin_amdgcn_mfma_f32_16x16x32_bf16(vv, pv, O[dt], 0, 0, 0); }
;         }
	v_mov_b32 v18, 0
	v_mov_b32 v19, 0
	s_nop 1
	s_nop 0
	v_cndmask_b32_e32 v55, 0, v10, vcc
	v_add_f32_e32 v8, v55, v8
	v_mov_b32_e32 v9, v8
	s_nop 1
	v_permlane16_swap_b32_e32 v8, v9
	v_add_f32_e32 v8, v8, v9
	v_mov_b32_e32 v9, v8
	s_nop 1
	v_permlane32_swap_b32_e32 v8, v9
	v_add_f32_e32 v8, v8, v9
	v_div_scale_f32 v9, s[4:5], v8, v8, 1.0
	v_rcp_f32_e32 v10, v9
	v_readlane_b32 s4, v255, 2
	v_fma_f32 v11, -v9, v10, 1.0
	v_fmac_f32_e32 v10, v11, v10
	v_div_scale_f32 v11, vcc, 1.0, v8, 1.0
	v_mul_f32_e32 v12, v11, v10
	v_fma_f32 v13, -v9, v12, v11
	v_fmac_f32_e32 v12, v13, v10
	v_fma_f32 v9, -v9, v12, v11
	v_div_fmas_f32 v9, v9, v10, v12
	v_div_fixup_f32 v9, v9, v8, 1.0
	v_cmp_lt_f32_e32 vcc, 0, v8
	v_add_u32_e32 v44, s4, v44
	s_movk_i32 s4, 0x210
	v_cndmask_b32_e32 v62, 0, v9, vcc
	v_mad_u32_u24 v119, v106, s4, v44
	v_pk_mul_f32 v[36:37], v[62:63], v[2:3] op_sel_hi:[0,1]
	v_pk_mul_f32 v[38:39], v[62:63], v[0:1] op_sel_hi:[0,1]
	v_pk_mul_f32 v[32:33], v[62:63], v[6:7] op_sel_hi:[0,1]
	v_pk_mul_f32 v[34:35], v[62:63], v[4:5] op_sel_hi:[0,1]
	v_add_u32_e32 v118, 0x2000, v119
	v_add_u32_e32 v117, 0x4000, v119
	v_add_u32_e32 v116, 0x6000, v119
	v_add_u32_e32 v115, 0x8000, v119
	v_add_u32_e32 v114, 0xa000, v119
	v_add_u32_e32 v113, 0xc000, v119
	v_add_u32_e32 v120, 0xe000, v119
	v_mov_b32 v12, 0
	v_mov_b32 v13, 0
	v_mov_b32 v14, 0
	v_mov_b32 v15, 0
	s_nop 1
	v_mov_b32 v8, 0
	v_mov_b32 v9, 0
	v_mov_b32 v10, 0
	v_mov_b32 v11, 0
	s_nop 1
	v_mov_b32 v4, 0
	v_mov_b32 v5, 0
	v_mov_b32 v6, 0
	v_mov_b32 v7, 0
	s_nop 1
	v_mov_b32 v0, 0
	v_mov_b32 v1, 0
	v_mov_b32 v2, 0
	v_mov_b32 v3, 0
	s_nop 1
	s_and_saveexec_b64 s[24:25], s[20:21]
	s_cbranch_execz .LBB0_138
	ds_read2_b64 v[130:133], v119 offset1:4
	ds_read2_b64 v[134:137], v118 offset0:32 offset1:36
	ds_read2_b64 v[138:141], v117 offset0:64 offset1:68
	ds_read2_b64 v[142:145], v116 offset0:96 offset1:100
	ds_read2_b64 v[146:149], v115 offset0:128 offset1:132
	ds_read2_b64 v[150:153], v114 offset0:160 offset1:164
	ds_read2_b64 v[154:157], v113 offset0:192 offset1:196
	ds_read2_b64 v[158:161], v120 offset0:224 offset1:228
	v_cvt_pk_bf16_f32 v122, v38, v39
	v_cvt_pk_bf16_f32 v123, v36, v37
	v_cvt_pk_bf16_f32 v124, v34, v35
	v_cvt_pk_bf16_f32 v125, v32, v33
	s_waitcnt lgkmcnt(7)
	s_nop 0
	v_mfma_f32_16x16x32_bf16 v[28:31], v[130:133], v[122:125], v[28:31]
	s_waitcnt lgkmcnt(6)
	v_mfma_f32_16x16x32_bf16 v[24:27], v[134:137], v[122:125], v[24:27]
	s_waitcnt lgkmcnt(5)
	v_mfma_f32_16x16x32_bf16 v[20:23], v[138:141], v[122:125], v[20:23]
	s_waitcnt lgkmcnt(4)
	v_mfma_f32_16x16x32_bf16 v[16:19], v[142:145], v[122:125], v[16:19]
	s_waitcnt lgkmcnt(3)
	v_mfma_f32_16x16x32_bf16 v[12:15], v[146:149], v[122:125], v[12:15]
	s_waitcnt lgkmcnt(2)
	v_mfma_f32_16x16x32_bf16 v[8:11], v[150:153], v[122:125], v[8:11]
	s_waitcnt lgkmcnt(1)
	v_mfma_f32_16x16x32_bf16 v[4:7], v[154:157], v[122:125], v[4:7]
	s_waitcnt lgkmcnt(0)
	v_mfma_f32_16x16x32_bf16 v[0:3], v[158:161], v[122:125], v[0:3]
.LBB0_138:
	s_or_b64 exec, exec, s[24:25]
	v_mov_b32_e32 v63, v62
	v_mov_b32_e32 v106, v62
	v_mov_b32_e32 v107, v62
	v_pk_mul_f32 v[44:45], v[106:107], v[42:43]
	v_pk_mul_f32 v[46:47], v[62:63], v[40:41]
	v_pk_mul_f32 v[40:41], v[106:107], v[66:67]
	v_pk_mul_f32 v[42:43], v[62:63], v[64:65]
	s_and_saveexec_b64 s[20:21], s[18:19]
	s_cbranch_execz .LBB0_140
	ds_read2_b64 v[162:165], v119 offset0:8 offset1:12
	ds_read2_b64 v[166:169], v118 offset0:40 offset1:44
	ds_read2_b64 v[170:173], v117 offset0:72 offset1:76
	ds_read2_b64 v[174:177], v116 offset0:104 offset1:108
	ds_read2_b64 v[178:181], v115 offset0:136 offset1:140
	ds_read2_b64 v[182:185], v114 offset0:168 offset1:172
	ds_read2_b64 v[186:189], v113 offset0:200 offset1:204
	ds_read2_b64 v[190:193], v120 offset0:232 offset1:236
	v_cvt_pk_bf16_f32 v122, v46, v47
	v_cvt_pk_bf16_f32 v123, v44, v45
	v_cvt_pk_bf16_f32 v124, v42, v43
	v_cvt_pk_bf16_f32 v125, v40, v41
	s_waitcnt lgkmcnt(7)
	s_nop 0
	v_mfma_f32_16x16x32_bf16 v[28:31], v[162:165], v[122:125], v[28:31]
	s_waitcnt lgkmcnt(6)
	v_mfma_f32_16x16x32_bf16 v[24:27], v[166:169], v[122:125], v[24:27]
	s_waitcnt lgkmcnt(5)
	v_mfma_f32_16x16x32_bf16 v[20:23], v[170:173], v[122:125], v[20:23]
	s_waitcnt lgkmcnt(4)
	v_mfma_f32_16x16x32_bf16 v[16:19], v[174:177], v[122:125], v[16:19]
	s_waitcnt lgkmcnt(3)
	v_mfma_f32_16x16x32_bf16 v[12:15], v[178:181], v[122:125], v[12:15]
	s_waitcnt lgkmcnt(2)
	v_mfma_f32_16x16x32_bf16 v[8:11], v[182:185], v[122:125], v[8:11]
	s_waitcnt lgkmcnt(1)
	v_mfma_f32_16x16x32_bf16 v[4:7], v[186:189], v[122:125], v[4:7]
	s_waitcnt lgkmcnt(0)
	v_mfma_f32_16x16x32_bf16 v[0:3], v[190:193], v[122:125], v[0:3]
.LBB0_140:
	s_or_b64 exec, exec, s[20:21]
	v_pk_mul_f32 v[64:65], v[106:107], v[58:59]
	v_pk_mul_f32 v[66:67], v[62:63], v[56:57]
	v_pk_mul_f32 v[56:57], v[106:107], v[90:91]
	v_pk_mul_f32 v[58:59], v[62:63], v[86:87]
	s_and_saveexec_b64 s[18:19], s[16:17]
	s_cbranch_execz .LBB0_142
	ds_read2_b64 v[130:133], v119 offset0:16 offset1:20
	ds_read2_b64 v[134:137], v118 offset0:48 offset1:52
	ds_read2_b64 v[138:141], v117 offset0:80 offset1:84
	ds_read2_b64 v[142:145], v116 offset0:112 offset1:116
	ds_read2_b64 v[146:149], v115 offset0:144 offset1:148
	ds_read2_b64 v[150:153], v114 offset0:176 offset1:180
	ds_read2_b64 v[154:157], v113 offset0:208 offset1:212
	ds_read2_b64 v[158:161], v120 offset0:240 offset1:244
	v_cvt_pk_bf16_f32 v126, v66, v67
	v_cvt_pk_bf16_f32 v127, v64, v65
	v_cvt_pk_bf16_f32 v128, v58, v59
	v_cvt_pk_bf16_f32 v129, v56, v57
	s_waitcnt lgkmcnt(7)
	s_nop 0
	v_mfma_f32_16x16x32_bf16 v[28:31], v[130:133], v[126:129], v[28:31]
	s_waitcnt lgkmcnt(6)
	v_mfma_f32_16x16x32_bf16 v[24:27], v[134:137], v[126:129], v[24:27]
	s_waitcnt lgkmcnt(5)
	v_mfma_f32_16x16x32_bf16 v[20:23], v[138:141], v[126:129], v[20:23]
	s_waitcnt lgkmcnt(4)
	v_mfma_f32_16x16x32_bf16 v[16:19], v[142:145], v[126:129], v[16:19]
	s_waitcnt lgkmcnt(3)
	v_mfma_f32_16x16x32_bf16 v[12:15], v[146:149], v[126:129], v[12:15]
	s_waitcnt lgkmcnt(2)
	v_mfma_f32_16x16x32_bf16 v[8:11], v[150:153], v[126:129], v[8:11]
	s_waitcnt lgkmcnt(1)
	v_mfma_f32_16x16x32_bf16 v[4:7], v[154:157], v[126:129], v[4:7]
	s_waitcnt lgkmcnt(0)
	v_mfma_f32_16x16x32_bf16 v[0:3], v[158:161], v[126:129], v[0:3]
; #define LAS __attribute__((address_space(3)))
; DI unsigned pk2(float lo, float hi) { f32x2 v = {lo, hi}; bf16v2 b = __builtin_convertvector(v, bf16v2); return __builtin_bit_cast(unsigned, b); }
; DI void cmp_item(const Params& p, int item, LAS unsigned char* lds, int tid) {
;     ...
;     for (int k2 = 0; k2 < 8; ++k2) {
;         if (2 * k2 < ntile) {
;             u32x4 pa; pa.x = pk2(acc[2 * k2][0], acc[2 * k2][1]); pa.y = pk2(acc[2 * k2][2], acc[2 * k2][3]); pa.z = pk2(acc[2 * k2 + 1][0], acc[2 * k2 + 1][1]); pa.w = pk2(acc[2 * k2 + 1][2], acc[2 * k2 + 1][3]);
;             const bf16x8 pv = __builtin_bit_cast(bf16x8, pa);
; #pragma unroll
;             for (int dt = 0; dt < 8; ++dt) { const LAS bf16_t* vp = vcL + (dt * 16 + i16) * 264 + k2 * 32 + quad * 4;
;                 const u32x2 lo = *(const LAS u32x2*)vp, hi = *(const LAS u32x2*)(vp + 16);
;                 const bf16x8 vv = __builtin_bit_cast(bf16x8, (u32x4){lo.x, lo.y, hi.x, hi.y});
;                 O[dt] = __builtin_amdgcn_mfma_f32_16x16x32_bf16(vv, pv, O[dt], 0, 0, 0); }
;         }
.LBB0_142:
	s_or_b64 exec, exec, s[18:19]
	v_mov_b32_e32 v106, v62
	v_mov_b32_e32 v107, v62
	v_pk_mul_f32 v[86:87], v[106:107], v[78:79]
	v_pk_mul_f32 v[90:91], v[62:63], v[76:77]
	v_pk_mul_f32 v[76:77], v[106:107], v[104:105]
	v_pk_mul_f32 v[78:79], v[62:63], v[100:101]
	s_and_saveexec_b64 s[16:17], s[14:15]
	s_cbranch_execz .LBB0_144
	ds_read2_b64 v[162:165], v119 offset0:24 offset1:28
	ds_read2_b64 v[166:169], v118 offset0:56 offset1:60
	ds_read2_b64 v[170:173], v117 offset0:88 offset1:92
	ds_read2_b64 v[174:177], v116 offset0:120 offset1:124
	ds_read2_b64 v[178:181], v115 offset0:152 offset1:156
	ds_read2_b64 v[182:185], v114 offset0:184 offset1:188
	ds_read2_b64 v[186:189], v113 offset0:216 offset1:220
	ds_read2_b64 v[190:193], v120 offset0:248 offset1:252
	v_cvt_pk_bf16_f32 v126, v90, v91
	v_cvt_pk_bf16_f32 v127, v86, v87
	v_cvt_pk_bf16_f32 v128, v78, v79
	v_cvt_pk_bf16_f32 v129, v76, v77
	s_waitcnt lgkmcnt(7)
	s_nop 0
	v_mfma_f32_16x16x32_bf16 v[28:31], v[162:165], v[126:129], v[28:31]
	s_waitcnt lgkmcnt(6)
	v_mfma_f32_16x16x32_bf16 v[24:27], v[166:169], v[126:129], v[24:27]
	s_waitcnt lgkmcnt(5)
	v_mfma_f32_16x16x32_bf16 v[20:23], v[170:173], v[126:129], v[20:23]
	s_waitcnt lgkmcnt(4)
	v_mfma_f32_16x16x32_bf16 v[16:19], v[174:177], v[126:129], v[16:19]
	s_waitcnt lgkmcnt(3)
	v_mfma_f32_16x16x32_bf16 v[12:15], v[178:181], v[126:129], v[12:15]
	s_waitcnt lgkmcnt(2)
	v_mfma_f32_16x16x32_bf16 v[8:11], v[182:185], v[126:129], v[8:11]
	s_waitcnt lgkmcnt(1)
	v_mfma_f32_16x16x32_bf16 v[4:7], v[186:189], v[126:129], v[4:7]
	s_waitcnt lgkmcnt(0)
	v_mfma_f32_16x16x32_bf16 v[0:3], v[190:193], v[126:129], v[0:3]
.LBB0_144:
	s_or_b64 exec, exec, s[16:17]
	v_pk_mul_f32 v[100:101], v[106:107], v[96:97]
	v_pk_mul_f32 v[104:105], v[62:63], v[94:95]
	v_pk_mul_f32 v[94:95], v[106:107], v[102:103]
	v_pk_mul_f32 v[96:97], v[62:63], v[98:99]
	v_add_u32_e32 v120, 0xe800, v119
	s_and_saveexec_b64 s[14:15], s[12:13]
	s_cbranch_execz .LBB0_146
	ds_read2_b64 v[130:133], v119 offset0:32 offset1:36
	ds_read2_b64 v[134:137], v118 offset0:64 offset1:68
	ds_read2_b64 v[138:141], v117 offset0:96 offset1:100
	ds_read2_b64 v[142:145], v116 offset0:128 offset1:132
	ds_read2_b64 v[146:149], v115 offset0:160 offset1:164
	ds_read2_b64 v[150:153], v114 offset0:192 offset1:196
	ds_read2_b64 v[154:157], v113 offset0:224 offset1:228
	ds_read2_b64 v[158:161], v120 offset1:4
	v_cvt_pk_bf16_f32 v126, v104, v105
	v_cvt_pk_bf16_f32 v127, v100, v101
	v_cvt_pk_bf16_f32 v128, v96, v97
	v_cvt_pk_bf16_f32 v129, v94, v95
	s_waitcnt lgkmcnt(7)
	s_nop 0
	v_mfma_f32_16x16x32_bf16 v[28:31], v[130:133], v[126:129], v[28:31]
	s_waitcnt lgkmcnt(6)
	v_mfma_f32_16x16x32_bf16 v[24:27], v[134:137], v[126:129], v[24:27]
	s_waitcnt lgkmcnt(5)
	v_mfma_f32_16x16x32_bf16 v[20:23], v[138:141], v[126:129], v[20:23]
	s_waitcnt lgkmcnt(4)
	v_mfma_f32_16x16x32_bf16 v[16:19], v[142:145], v[126:129], v[16:19]
	s_waitcnt lgkmcnt(3)
	v_mfma_f32_16x16x32_bf16 v[12:15], v[146:149], v[126:129], v[12:15]
	s_waitcnt lgkmcnt(2)
	v_mfma_f32_16x16x32_bf16 v[8:11], v[150:153], v[126:129], v[8:11]
	s_waitcnt lgkmcnt(1)
	v_mfma_f32_16x16x32_bf16 v[4:7], v[154:157], v[126:129], v[4:7]
	s_waitcnt lgkmcnt(0)
	v_mfma_f32_16x16x32_bf16 v[0:3], v[158:161], v[126:129], v[0:3]
; #define LAS __attribute__((address_space(3)))
; DI unsigned pk2(float lo, float hi) { f32x2 v = {lo, hi}; bf16v2 b = __builtin_convertvector(v, bf16v2); return __builtin_bit_cast(unsigned, b); }
; DI void cmp_item(const Params& p, int item, LAS unsigned char* lds, int tid) {
;     ...
;     for (int k2 = 0; k2 < 8; ++k2) {
;         if (2 * k2 < ntile) {
;             u32x4 pa; pa.x = pk2(acc[2 * k2][0], acc[2 * k2][1]); pa.y = pk2(acc[2 * k2][2], acc[2 * k2][3]); pa.z = pk2(acc[2 * k2 + 1][0], acc[2 * k2 + 1][1]); pa.w = pk2(acc[2 * k2 + 1][2], acc[2 * k2 + 1][3]);
;             const bf16x8 pv = __builtin_bit_cast(bf16x8, pa);
; #pragma unroll
;             for (int dt = 0; dt < 8; ++dt) { const LAS bf16_t* vp = vcL + (dt * 16 + i16) * 264 + k2 * 32 + quad * 4;
;                 const u32x2 lo = *(const LAS u32x2*)vp, hi = *(const LAS u32x2*)(vp + 16);
;                 const bf16x8 vv = __builtin_bit_cast(bf16x8, (u32x4){lo.x, lo.y, hi.x, hi.y});
;                 O[dt] = __builtin_amdgcn_mfma_f32_16x16x32_bf16(vv, pv, O[dt], 0, 0, 0); }
;         }
.LBB0_146:
	s_or_b64 exec, exec, s[14:15]
	v_mov_b32_e32 v106, v62
	v_mov_b32_e32 v107, v62
	v_pk_mul_f32 v[98:99], v[106:107], v[84:85]
	v_pk_mul_f32 v[102:103], v[62:63], v[74:75]
	v_pk_mul_f32 v[74:75], v[106:107], v[92:93]
	v_pk_mul_f32 v[84:85], v[62:63], v[88:89]
	s_and_saveexec_b64 s[12:13], s[10:11]
	s_cbranch_execz .LBB0_148
	ds_read2_b64 v[162:165], v119 offset0:40 offset1:44
	ds_read2_b64 v[166:169], v118 offset0:72 offset1:76
	ds_read2_b64 v[170:173], v117 offset0:104 offset1:108
	ds_read2_b64 v[174:177], v116 offset0:136 offset1:140
	ds_read2_b64 v[178:181], v115 offset0:168 offset1:172
	ds_read2_b64 v[182:185], v114 offset0:200 offset1:204
	ds_read2_b64 v[186:189], v113 offset0:232 offset1:236
	ds_read2_b64 v[190:193], v120 offset0:8 offset1:12
	v_cvt_pk_bf16_f32 v126, v102, v103
	v_cvt_pk_bf16_f32 v127, v98, v99
	v_cvt_pk_bf16_f32 v128, v84, v85
	v_cvt_pk_bf16_f32 v129, v74, v75
	s_waitcnt lgkmcnt(7)
	s_nop 0
	v_mfma_f32_16x16x32_bf16 v[28:31], v[162:165], v[126:129], v[28:31]
	s_waitcnt lgkmcnt(6)
	v_mfma_f32_16x16x32_bf16 v[24:27], v[166:169], v[126:129], v[24:27]
	s_waitcnt lgkmcnt(5)
	v_mfma_f32_16x16x32_bf16 v[20:23], v[170:173], v[126:129], v[20:23]
	s_waitcnt lgkmcnt(4)
	v_mfma_f32_16x16x32_bf16 v[16:19], v[174:177], v[126:129], v[16:19]
	s_waitcnt lgkmcnt(3)
	v_mfma_f32_16x16x32_bf16 v[12:15], v[178:181], v[126:129], v[12:15]
	s_waitcnt lgkmcnt(2)
	v_mfma_f32_16x16x32_bf16 v[8:11], v[182:185], v[126:129], v[8:11]
	s_waitcnt lgkmcnt(1)
	v_mfma_f32_16x16x32_bf16 v[4:7], v[186:189], v[126:129], v[4:7]
	s_waitcnt lgkmcnt(0)
	v_mfma_f32_16x16x32_bf16 v[0:3], v[190:193], v[126:129], v[0:3]
.LBB0_148:
	s_or_b64 exec, exec, s[12:13]
	v_pk_mul_f32 v[88:89], v[106:107], v[68:69]
	v_pk_mul_f32 v[92:93], v[62:63], v[60:61]
	v_pk_mul_f32 v[60:61], v[106:107], v[72:73]
	v_pk_mul_f32 v[68:69], v[62:63], v[70:71]
	s_and_saveexec_b64 s[10:11], s[8:9]
	s_cbranch_execz .LBB0_150
	ds_read2_b64 v[130:133], v119 offset0:48 offset1:52
	ds_read2_b64 v[134:137], v118 offset0:80 offset1:84
	ds_read2_b64 v[138:141], v117 offset0:112 offset1:116
	ds_read2_b64 v[142:145], v116 offset0:144 offset1:148
	ds_read2_b64 v[146:149], v115 offset0:176 offset1:180
	ds_read2_b64 v[150:153], v114 offset0:208 offset1:212
	ds_read2_b64 v[154:157], v113 offset0:240 offset1:244
	ds_read2_b64 v[158:161], v120 offset0:16 offset1:20
	v_cvt_pk_bf16_f32 v122, v92, v93
	v_cvt_pk_bf16_f32 v123, v88, v89
	v_cvt_pk_bf16_f32 v124, v68, v69
	v_cvt_pk_bf16_f32 v125, v60, v61
	s_waitcnt lgkmcnt(7)
	s_nop 0
	v_mfma_f32_16x16x32_bf16 v[28:31], v[130:133], v[122:125], v[28:31]
	s_waitcnt lgkmcnt(6)
	v_mfma_f32_16x16x32_bf16 v[24:27], v[134:137], v[122:125], v[24:27]
	s_waitcnt lgkmcnt(5)
	v_mfma_f32_16x16x32_bf16 v[20:23], v[138:141], v[122:125], v[20:23]
	s_waitcnt lgkmcnt(4)
	v_mfma_f32_16x16x32_bf16 v[16:19], v[142:145], v[122:125], v[16:19]
	s_waitcnt lgkmcnt(3)
	v_mfma_f32_16x16x32_bf16 v[12:15], v[146:149], v[122:125], v[12:15]
	s_waitcnt lgkmcnt(2)
	v_mfma_f32_16x16x32_bf16 v[8:11], v[150:153], v[122:125], v[8:11]
	s_waitcnt lgkmcnt(1)
	v_mfma_f32_16x16x32_bf16 v[4:7], v[154:157], v[122:125], v[4:7]
	s_waitcnt lgkmcnt(0)
	v_mfma_f32_16x16x32_bf16 v[0:3], v[158:161], v[122:125], v[0:3]
.LBB0_150:
	s_or_b64 exec, exec, s[10:11]
	v_mov_b32_e32 v106, v62
	v_mov_b32_e32 v107, v62
	v_pk_mul_f32 v[70:71], v[106:107], v[50:51]
	v_pk_mul_f32 v[72:73], v[62:63], v[48:49]
	v_pk_mul_f32 v[48:49], v[106:107], v[54:55]
	v_pk_mul_f32 v[50:51], v[62:63], v[52:53]
	s_and_saveexec_b64 s[8:9], s[6:7]
	s_cbranch_execz .LBB0_152
	ds_read2_b64 v[162:165], v119 offset0:56 offset1:60
	ds_read2_b64 v[166:169], v118 offset0:88 offset1:92
	ds_read2_b64 v[170:173], v117 offset0:120 offset1:124
	ds_read2_b64 v[174:177], v116 offset0:152 offset1:156
	ds_read2_b64 v[178:181], v115 offset0:184 offset1:188
	ds_read2_b64 v[182:185], v114 offset0:216 offset1:220
	ds_read2_b64 v[186:189], v113 offset0:248 offset1:252
	ds_read2_b64 v[190:193], v120 offset0:24 offset1:28
	v_cvt_pk_bf16_f32 v122, v72, v73
	v_cvt_pk_bf16_f32 v123, v70, v71
	v_cvt_pk_bf16_f32 v124, v50, v51
	v_cvt_pk_bf16_f32 v125, v48, v49
	s_waitcnt lgkmcnt(7)
	s_nop 0
	v_mfma_f32_16x16x32_bf16 v[28:31], v[162:165], v[122:125], v[28:31]
	s_waitcnt lgkmcnt(6)
	v_mfma_f32_16x16x32_bf16 v[24:27], v[166:169], v[122:125], v[24:27]
	s_waitcnt lgkmcnt(5)
	v_mfma_f32_16x16x32_bf16 v[20:23], v[170:173], v[122:125], v[20:23]
	s_waitcnt lgkmcnt(4)
	v_mfma_f32_16x16x32_bf16 v[16:19], v[174:177], v[122:125], v[16:19]
	s_waitcnt lgkmcnt(3)
	v_mfma_f32_16x16x32_bf16 v[12:15], v[178:181], v[122:125], v[12:15]
	s_waitcnt lgkmcnt(2)
	v_mfma_f32_16x16x32_bf16 v[8:11], v[182:185], v[122:125], v[8:11]
	s_waitcnt lgkmcnt(1)
	v_mfma_f32_16x16x32_bf16 v[4:7], v[186:189], v[122:125], v[4:7]
	s_waitcnt lgkmcnt(0)
	v_mfma_f32_16x16x32_bf16 v[0:3], v[190:193], v[122:125], v[0:3]
